# stack: epilogue base+imm addressing, row-stat loads issued before the align barrier, MFMA hand-off trim (prio before opening barrier, closing barrier 2 MFMAs early at prio 2)
# baseline (speedup 1.0000x reference)
.LBB0_259:
	v_mov_b32_e32 v130, v136
	v_mov_b32_e32 v145, v210
	v_readlane_b32 s0, v248, 15
	v_add_u32_e32 v130, s72, v130
	v_lshl_add_u32 v146, s91, 8, v130
	v_lshlrev_b32_e32 v148, 2, v145
	v_ashrrev_i32_e32 v149, 31, v148
	v_readlane_b32 s1, v248, 16
	v_ashrrev_i32_e32 v147, 31, v146
	v_lshlrev_b64 v[146:147], 6, v[146:147]
	v_lshl_add_u64 v[148:149], v[148:149], 2, s[0:1]
	v_lshl_add_u64 v[146:147], v[148:149], 0, v[146:147]
	v_lshl_add_u64 v[184:185], v[146:147], 0, 0
	global_load_dwordx4 v[148:151], v[146:147], off
	s_mov_b32 s98, 0x1000
	s_mov_b32 s99, 0x0
	v_lshl_add_u64 v[186:187], v[184:185], 0, s[98:99]
	global_load_dwordx4 v[152:155], v[186:187], off offset:-3072
	global_load_dwordx4 v[156:159], v[186:187], off offset:-2048
	global_load_dwordx4 v[160:163], v[186:187], off offset:-1024
	s_movk_i32 s0, 0x2000
	v_add_co_u32_e32 v146, vcc, s0, v146
	v_xor_b32_e32 v180, 32, v143
	s_nop 0
	v_addc_co_u32_e32 v147, vcc, 0, v147, vcc
	s_mov_b32 s98, 0x3000
	s_mov_b32 s99, 0x0
	v_lshl_add_u64 v[186:187], v[184:185], 0, s[98:99]
	global_load_dwordx4 v[164:167], v[186:187], off offset:-4096
	global_load_dwordx4 v[168:171], v[186:187], off offset:-3072
	global_load_dwordx4 v[172:175], v[186:187], off offset:-2048
	global_load_dwordx4 v[176:179], v[186:187], off offset:-1024
	s_and_b64 vcc, exec, s[16:17]
	s_cbranch_vccz .LBB0_261
	s_barrier
.LBB0_261:
	v_and_b32_e32 v147, 64, v143
	v_xor_b32_e32 v146, 16, v143
	v_add_u32_e32 v147, 64, v147
	v_cmp_lt_i32_e32 vcc, v146, v147
	s_mul_i32 s0, s91, 44
	s_lshl_b32 s1, s10, 1
	v_cndmask_b32_e32 v146, v143, v146, vcc
	v_cmp_lt_i32_e32 vcc, v180, v147
	v_lshlrev_b32_e32 v182, 2, v146
	s_add_i32 s0, s0, s1
	v_cndmask_b32_e32 v147, v143, v180, vcc
	v_lshl_add_u32 v180, v145, 3, s80
	v_ashrrev_i32_e32 v146, 5, v180
	v_lshlrev_b32_e32 v183, 2, v147
	s_or_b32 s0, s0, s79
	s_ashr_i32 s1, s0, 31
	s_lshl_b64 s[0:1], s[0:1], 15
	v_lshlrev_b32_e32 v145, 4, v145
	s_add_u32 s50, s70, s0
	v_and_b32_e32 v145, 48, v145
	s_addc_u32 s51, s71, s1
	s_cmpk_lt_i32 s91, 0x80
	s_cselect_b64 s[0:1], -1, 0
	s_xor_b64 s[52:53], s[36:37], -1
	s_and_b64 s[52:53], s[52:53], s[0:1]
	s_mov_b64 s[6:7], -1
	s_and_b64 vcc, exec, s[52:53]
	s_waitcnt vmcnt(7)
	v_mov_b32_e32 v180, v149
	v_mov_b32_e32 v181, v150
	v_mov_b32_e32 v149, v151
	s_waitcnt vmcnt(6)
	v_add_f32_e32 v147, v152, v153
	v_add_f32_e32 v150, v154, v155
	s_waitcnt vmcnt(5)
	v_add_f32_e32 v151, v156, v157
	v_add_f32_e32 v152, v158, v159
	s_waitcnt vmcnt(4)
	v_add_f32_e32 v153, v160, v161
	v_add_f32_e32 v154, v162, v163
	v_pk_add_f32 v[148:149], v[180:181], v[148:149]
	v_add_f32_e32 v147, v147, v150
	v_add_f32_e32 v150, v151, v152
	v_add_f32_e32 v151, v153, v154
	s_waitcnt vmcnt(3)
	v_add_f32_e32 v152, v164, v165
	v_add_f32_e32 v153, v166, v167
	v_add_f32_e32 v148, v148, v149
	v_add_f32_e32 v152, v152, v153
	ds_bpermute_b32 v153, v182, v148
	ds_bpermute_b32 v160, v182, v150
	s_waitcnt vmcnt(1)
	v_add_f32_e32 v156, v172, v173
	v_add_f32_e32 v157, v174, v175
	v_add_f32_e32 v162, v156, v157
	s_waitcnt lgkmcnt(1)
	v_add_f32_e32 v148, v148, v153
	s_waitcnt lgkmcnt(0)
	v_add_f32_e32 v157, v150, v160
	ds_bpermute_b32 v150, v183, v148
	ds_bpermute_b32 v149, v182, v147
	ds_bpermute_b32 v166, v182, v162
	v_add_f32_e32 v154, v168, v169
	v_add_f32_e32 v155, v170, v171
	s_waitcnt lgkmcnt(2)
	v_add_f32_e32 v148, v148, v150
	s_waitcnt vmcnt(0)
	v_add_f32_e32 v158, v176, v177
	v_add_f32_e32 v159, v178, v179
	v_add_f32_e32 v154, v154, v155
	v_fmamk_f32 v148, v148, 0x3a800000, v144
	ds_bpermute_b32 v161, v182, v151
	v_add_f32_e32 v163, v158, v159
	ds_bpermute_b32 v164, v182, v152
	ds_bpermute_b32 v165, v182, v154
	s_waitcnt lgkmcnt(4)
	v_add_f32_e32 v159, v147, v149
	s_waitcnt lgkmcnt(3)
	v_add_f32_e32 v149, v162, v166
	v_rsq_f32_e32 v162, v148
	ds_bpermute_b32 v167, v182, v163
	s_waitcnt lgkmcnt(3)
	v_add_f32_e32 v155, v151, v161
	s_waitcnt lgkmcnt(2)
	v_add_f32_e32 v153, v152, v164
	v_pk_mul_f32 v[122:123], v[122:123], v[162:163] op_sel_hi:[1,0]
	s_waitcnt lgkmcnt(1)
	v_add_f32_e32 v151, v154, v165
	v_pk_mul_f32 v[124:125], v[124:125], v[162:163] op_sel_hi:[1,0]
	v_pk_mul_f32 v[164:165], v[122:123], s[24:25] op_sel_hi:[1,0]
	s_waitcnt lgkmcnt(0)
	v_add_f32_e32 v147, v163, v167
	v_pk_mul_f32 v[166:167], v[124:125], s[24:25] op_sel_hi:[1,0]
	v_exp_f32_e32 v164, v164
	v_exp_f32_e32 v165, v165
	v_exp_f32_e32 v166, v166
	v_exp_f32_e32 v167, v167
	v_pk_mul_f32 v[126:127], v[126:127], v[162:163] op_sel_hi:[1,0]
	v_pk_add_f32 v[164:165], v[164:165], 1.0 op_sel_hi:[1,0]
	v_pk_mul_f32 v[114:115], v[114:115], v[162:163] op_sel_hi:[1,0]
	v_pk_add_f32 v[166:167], v[166:167], 1.0 op_sel_hi:[1,0]
	v_rcp_f32_e32 v164, v164
	v_rcp_f32_e32 v165, v165
	v_rcp_f32_e32 v166, v166
	v_rcp_f32_e32 v167, v167
	v_pk_mul_f32 v[128:129], v[128:129], v[162:163] op_sel_hi:[1,0]
	v_pk_mul_f32 v[122:123], v[122:123], v[164:165]
	v_pk_mul_f32 v[116:117], v[116:117], v[162:163] op_sel_hi:[1,0]
	v_pk_mul_f32 v[124:125], v[124:125], v[166:167]
	v_pk_mul_f32 v[122:123], v[126:127], v[122:123]
	v_pk_mul_f32 v[126:127], v[114:115], s[24:25] op_sel_hi:[1,0]
	v_pk_mul_f32 v[124:125], v[128:129], v[124:125]
	v_exp_f32_e32 v126, v126
	v_exp_f32_e32 v127, v127
	v_pk_mul_f32 v[128:129], v[116:117], s[24:25] op_sel_hi:[1,0]
	v_pk_mul_f32 v[118:119], v[118:119], v[162:163] op_sel_hi:[1,0]
	v_exp_f32_e32 v128, v128
	v_exp_f32_e32 v129, v129
	v_pk_add_f32 v[126:127], v[126:127], 1.0 op_sel_hi:[1,0]
	ds_bpermute_b32 v160, v183, v159
	v_rcp_f32_e32 v126, v126
	v_rcp_f32_e32 v127, v127
	v_pk_add_f32 v[128:129], v[128:129], 1.0 op_sel_hi:[1,0]
	ds_bpermute_b32 v158, v183, v157
	v_rcp_f32_e32 v128, v128
	v_rcp_f32_e32 v129, v129
	v_pk_mul_f32 v[114:115], v[114:115], v[126:127]
	ds_bpermute_b32 v156, v183, v155
	v_pk_mul_f32 v[126:127], v[118:119], v[114:115]
	v_pk_mul_f32 v[114:115], v[120:121], v[162:163] op_sel_hi:[1,0]
	v_pk_mul_f32 v[116:117], v[116:117], v[128:129]
	ds_bpermute_b32 v154, v183, v153
	v_pk_mul_f32 v[128:129], v[114:115], v[116:117]
	v_lshrrev_b32_e32 v115, 3, v130
	v_lshlrev_b32_e32 v114, 7, v130
	v_and_b32_e32 v115, 14, v115
	ds_bpermute_b32 v152, v183, v151
	ds_bpermute_b32 v150, v183, v149
	ds_bpermute_b32 v148, v183, v147
	v_and_b32_e32 v114, 0xffffc000, v114
	v_lshlrev_b32_e32 v116, 6, v130
	v_add_lshl_u32 v120, v115, v146, 10
	v_lshlrev_b32_e32 v115, 2, v130
	v_and_or_b32 v116, v116, s73, v145
	v_and_b32_e32 v115, 32, v115
	v_add_u32_e32 v114, v120, v114
	v_bitop3_b32 v114, v114, v116, v115 bitop3:0xf6
	v_ashrrev_i32_e32 v115, 31, v114
	v_lshl_add_u64 v[118:119], s[50:51], 0, v[114:115]
	v_cvt_pk_bf16_f32 v114, v122, v123
	v_cvt_pk_bf16_f32 v115, v124, v125
	v_cvt_pk_bf16_f32 v116, v126, v127
	v_cvt_pk_bf16_f32 v117, v128, v129
	v_lshl_add_u64 v[184:185], v[118:119], 0, 0
	s_cbranch_vccz .LBB0_263
	global_store_dwordx4 v[118:119], v[114:117], off
	s_mov_b64 s[6:7], 0

.LBB0_639:
	s_lshl_b32 s0, s31, 8
	v_mov_b32_e32 v223, v210
	v_mov_b32_e32 v220, v214
	s_add_i32 s0, s0, s81
	v_and_b32_e32 v153, 64, v216
	v_add_u32_e32 v178, s0, v220
	v_lshlrev_b32_e32 v130, 2, v223
	v_ashrrev_i32_e32 v131, 31, v130
	v_ashrrev_i32_e32 v179, 31, v178
	v_lshl_add_u64 v[130:131], v[130:131], 2, s[46:47]
	v_lshlrev_b64 v[206:207], 6, v[178:179]
	v_add_u32_e32 v174, 16, v178
	v_lshl_add_u64 v[132:133], v[130:131], 0, v[206:207]
	v_ashrrev_i32_e32 v175, 31, v174
	v_lshl_add_u64 v[250:251], v[132:133], 0, 0
	global_load_dwordx4 v[134:137], v[132:133], off
	v_lshlrev_b64 v[204:205], 6, v[174:175]
	v_add_u32_e32 v170, 32, v178
	v_ashrrev_i32_e32 v171, 31, v170
	s_mov_b32 s98, 0x1000
	s_mov_b32 s99, 0x0
	v_lshl_add_u64 v[252:253], v[250:251], 0, s[98:99]
	global_load_dwordx4 v[138:141], v[252:253], off offset:-3072
	v_lshlrev_b64 v[202:203], 6, v[170:171]
	v_add_u32_e32 v166, 48, v178
	v_ashrrev_i32_e32 v167, 31, v166
	global_load_dwordx4 v[142:145], v[252:253], off offset:-2048
	v_lshlrev_b64 v[192:193], 6, v[166:167]
	v_add_u32_e32 v162, 0x80, v178
	v_ashrrev_i32_e32 v163, 31, v162
	global_load_dwordx4 v[146:149], v[252:253], off offset:-1024
	v_lshlrev_b64 v[190:191], 6, v[162:163]
	v_add_u32_e32 v158, 0x90, v178
	v_ashrrev_i32_e32 v159, 31, v158
	s_mov_b32 s98, 0x3000
	s_mov_b32 s99, 0x0
	v_lshl_add_u64 v[252:253], v[250:251], 0, s[98:99]
	global_load_dwordx4 v[180:183], v[252:253], off offset:-4096
	v_lshlrev_b64 v[188:189], 6, v[158:159]
	v_add_u32_e32 v154, 0xa0, v178
	v_add_u32_e32 v150, 0xb0, v178
	v_ashrrev_i32_e32 v155, 31, v154
	v_ashrrev_i32_e32 v151, 31, v150
	global_load_dwordx4 v[224:227], v[252:253], off offset:-3072
	v_lshlrev_b64 v[186:187], 6, v[154:155]
	v_lshlrev_b64 v[184:185], 6, v[150:151]
	global_load_dwordx4 v[228:231], v[252:253], off offset:-2048
	v_xor_b32_e32 v152, 16, v216
	global_load_dwordx4 v[130:133], v[252:253], off offset:-1024
	s_and_b64 vcc, exec, s[96:97]
	s_cbranch_vccz .LBB0_641
	s_barrier
.LBB0_641:
	v_add_u32_e32 v153, 64, v153
	v_cmp_lt_i32_e32 vcc, v152, v153
	s_cmp_lt_u32 s38, 6
	s_cselect_b32 s0, 2, 3
	v_cndmask_b32_e32 v152, v216, v152, vcc
	v_lshlrev_b32_e32 v221, 2, v152
	v_xor_b32_e32 v152, 32, v216
	v_cmp_lt_i32_e32 vcc, v152, v153
	s_cselect_b32 s1, -4, -6
	s_cmp_lt_u32 s38, 4
	v_cndmask_b32_e32 v152, v216, v152, vcc
	v_lshlrev_b32_e32 v222, 2, v152
	s_cselect_b32 s0, 1, s0
	s_cselect_b32 s1, -2, s1
	s_cmp_lt_i32 s38, 2
	s_cselect_b32 s3, 0, s0
	s_cselect_b32 s0, 0, s1
	s_add_i32 s0, s0, s38
	s_cmp_lt_i32 s3, 2
	s_waitcnt vmcnt(7)
	v_add_f32_e32 v134, v134, v135
	v_add_f32_e32 v135, v136, v137
	v_add_f32_e32 v134, v134, v135
	ds_bpermute_b32 v135, v221, v134
	s_waitcnt vmcnt(6)
	v_add_f32_e32 v136, v138, v139
	v_add_f32_e32 v137, v140, v141
	v_add_f32_e32 v136, v136, v137
	ds_bpermute_b32 v137, v221, v136
	s_waitcnt lgkmcnt(1)
	v_add_f32_e32 v134, v134, v135
	s_waitcnt vmcnt(5)
	v_add_f32_e32 v138, v142, v143
	v_add_f32_e32 v139, v144, v145
	v_add_f32_e32 v138, v138, v139
	ds_bpermute_b32 v139, v221, v138
	ds_bpermute_b32 v135, v222, v134
	s_waitcnt vmcnt(4)
	v_add_f32_e32 v140, v146, v147
	v_add_f32_e32 v141, v148, v149
	v_add_f32_e32 v140, v140, v141
	ds_bpermute_b32 v141, v221, v140
	s_waitcnt lgkmcnt(3)
	v_add_f32_e32 v136, v136, v137
	s_waitcnt vmcnt(3)
	v_add_f32_e32 v142, v180, v181
	v_add_f32_e32 v143, v182, v183
	v_add_f32_e32 v142, v142, v143
	ds_bpermute_b32 v137, v222, v136
	ds_bpermute_b32 v143, v221, v142
	s_waitcnt lgkmcnt(4)
	v_add_f32_e32 v138, v138, v139
	ds_bpermute_b32 v139, v222, v138
	s_waitcnt vmcnt(2)
	v_add_f32_e32 v144, v224, v225
	v_add_f32_e32 v145, v226, v227
	v_add_f32_e32 v144, v144, v145
	ds_bpermute_b32 v145, v221, v144
	s_waitcnt lgkmcnt(4)
	v_add_f32_e32 v140, v140, v141
	s_waitcnt vmcnt(1)
	v_add_f32_e32 v146, v228, v229
	v_add_f32_e32 v147, v230, v231
	s_waitcnt vmcnt(0)
	v_add_f32_e32 v130, v130, v131
	v_add_f32_e32 v131, v132, v133
	v_add_f32_e32 v146, v146, v147
	v_add_f32_e32 v130, v130, v131
	v_add_f32_e32 v132, v134, v135
	ds_bpermute_b32 v141, v222, v140
	ds_bpermute_b32 v147, v221, v146
	ds_bpermute_b32 v131, v221, v130
	v_fmamk_f32 v132, v132, 0x3a800000, v217
	s_waitcnt lgkmcnt(5)
	v_add_f32_e32 v142, v142, v143
	v_rsq_f32_e32 v180, v132
	v_add_f32_e32 v132, v136, v137
	ds_bpermute_b32 v143, v222, v142
	v_fmamk_f32 v132, v132, 0x3a800000, v217
	s_waitcnt lgkmcnt(4)
	v_add_f32_e32 v144, v144, v145
	v_rsq_f32_e32 v176, v132
	v_add_f32_e32 v132, v138, v139
	ds_bpermute_b32 v145, v222, v144
	v_fmamk_f32 v132, v132, 0x3a800000, v217
	s_waitcnt lgkmcnt(3)
	v_add_f32_e32 v146, v146, v147
	s_waitcnt lgkmcnt(2)
	v_add_f32_e32 v130, v130, v131
	v_rsq_f32_e32 v172, v132
	v_add_f32_e32 v132, v140, v141
	ds_bpermute_b32 v147, v222, v146
	ds_bpermute_b32 v131, v222, v130
	v_fmamk_f32 v132, v132, 0x3a800000, v217
	v_rsq_f32_e32 v168, v132
	s_waitcnt lgkmcnt(3)
	v_add_f32_e32 v132, v142, v143
	v_fmamk_f32 v132, v132, 0x3a800000, v217
	v_rsq_f32_e32 v164, v132
	s_waitcnt lgkmcnt(2)
	v_add_f32_e32 v132, v144, v145
	v_fmamk_f32 v132, v132, 0x3a800000, v217
	v_rsq_f32_e32 v160, v132
	s_waitcnt lgkmcnt(1)
	v_add_f32_e32 v132, v146, v147
	s_waitcnt lgkmcnt(0)
	v_add_f32_e32 v130, v130, v131
	v_fmamk_f32 v132, v132, 0x3a800000, v217
	v_fmamk_f32 v130, v130, 0x3a800000, v217
	v_rsq_f32_e32 v156, v132
	v_rsq_f32_e32 v152, v130
	v_lshl_add_u32 v148, v223, 3, s82
	v_lshl_add_u32 v182, s0, 8, v148
	s_mov_b64 s[0:1], -1
	s_cbranch_scc1 .LBB0_727
	s_cmp_gt_i32 s3, 2
	s_cbranch_scc0 .LBB0_708
	s_mov_b32 s33, s64
	s_mov_b32 s15, s62
	s_mov_b64 s[28:29], s[58:59]
	s_mov_b64 s[26:27], s[56:57]
	s_mov_b32 s13, s63
	v_readlane_b32 s56, v249, 6
	v_ashrrev_i32_e32 v183, 31, v182
	v_readlane_b32 s64, v249, 14
	v_readlane_b32 s65, v249, 15
	v_lshrrev_b32_e32 v147, 3, v178
	v_lshlrev_b32_e32 v146, 1, v148
	v_lshl_add_u64 v[134:135], v[182:183], 2, s[64:65]
	s_mov_b32 s98, 0x10
	s_mov_b32 s99, 0x0
	v_lshl_add_u64 v[250:251], v[134:135], 0, s[98:99]
	global_load_dwordx4 v[138:141], v[134:135], off offset:16
	s_mov_b32 s98, 0xfffff000
	s_mov_b32 s99, 0xffffffff
	v_lshl_add_u64 v[252:253], v[250:251], 0, s[98:99]
	global_load_dwordx4 v[142:145], v[252:253], off offset:4080
	s_mov_b32 s98, 0x1000
	s_mov_b32 s99, 0x0
	v_lshl_add_u64 v[252:253], v[250:251], 0, s[98:99]
	global_load_dwordx4 v[130:133], v[252:253], off offset:-3584
	s_nop 0
	global_load_dwordx4 v[134:137], v[252:253], off offset:-3600
	v_bfe_u32 v183, v148, 5, 1
	v_and_or_b32 v147, v147, 14, v183
	v_and_b32_e32 v153, 48, v146
	v_ashrrev_i32_e32 v146, 3, v178
	v_lshlrev_b32_e32 v148, 6, v178
	v_lshlrev_b32_e32 v157, 10, v147
	v_lshlrev_b32_e32 v147, 2, v178
	v_and_b32_e32 v161, 0xffffffe0, v146
	v_lshlrev_b32_e32 v146, 7, v178
	v_and_b32_e32 v148, 0x3c0, v148
	v_and_b32_e32 v147, 32, v147
	v_and_b32_e32 v146, 0x4000, v146
	v_bitop3_b32 v147, v153, v147, v148 bitop3:0x36
	v_or3_b32 v198, v146, v147, v157
	v_ashrrev_i32_e32 v224, 6, v182
	s_cmpk_lt_i32 s31, 0x80
	s_cselect_b64 s[0:1], -1, 0
	s_xor_b64 s[22:23], s[36:37], -1
	s_and_b64 s[22:23], s[22:23], s[0:1]
	s_mov_b64 s[24:25], -1
	s_and_b64 vcc, exec, s[22:23]
	v_readlane_b32 s57, v249, 7
	v_readlane_b32 s58, v249, 8
	v_readlane_b32 s59, v249, 9
	v_readlane_b32 s60, v249, 10
	v_readlane_b32 s61, v249, 11
	v_readlane_b32 s62, v249, 12
	v_readlane_b32 s63, v249, 13
	v_readlane_b32 s66, v249, 16
	v_readlane_b32 s67, v249, 17
	v_readlane_b32 s68, v249, 18
	v_readlane_b32 s69, v249, 19
	v_readlane_b32 s70, v249, 20
	v_readlane_b32 s71, v249, 21
	s_waitcnt vmcnt(2)
	v_pk_fma_f32 v[146:147], v[126:127], v[180:181], v[142:143] op_sel_hi:[1,0,1]
	s_nop 0
	v_pk_mul_f32 v[146:147], v[146:147], s[94:95] op_sel_hi:[1,0]
	s_nop 0
	v_exp_f32_e32 v146, v146
	v_exp_f32_e32 v147, v147
	s_nop 0
	v_pk_add_f32 v[146:147], v[146:147], 1.0 op_sel_hi:[1,0]
	s_nop 0
	v_rcp_f32_e32 v148, v146
	v_rcp_f32_e32 v149, v147
	v_pk_fma_f32 v[146:147], v[128:129], v[180:181], v[144:145] op_sel_hi:[1,0,1]
	s_nop 0
	v_pk_mul_f32 v[146:147], v[146:147], s[94:95] op_sel_hi:[1,0]
	s_nop 0
	v_exp_f32_e32 v146, v146
	v_exp_f32_e32 v147, v147
	s_nop 0
	v_pk_add_f32 v[146:147], v[146:147], 1.0 op_sel_hi:[1,0]
	s_nop 0
	v_rcp_f32_e32 v165, v146
	v_rcp_f32_e32 v169, v147
	v_pk_fma_f32 v[146:147], v[122:123], v[180:181], v[138:139] op_sel_hi:[1,0,1]
	s_nop 0
	v_pk_mul_f32 v[146:147], v[146:147], s[94:95] op_sel_hi:[1,0]
	s_nop 0
	v_exp_f32_e32 v146, v146
	v_exp_f32_e32 v147, v147
	s_nop 0
	v_pk_add_f32 v[146:147], v[146:147], 1.0 op_sel_hi:[1,0]
	s_nop 0
	v_rcp_f32_e32 v173, v146
	v_rcp_f32_e32 v177, v147
	v_pk_fma_f32 v[146:147], v[124:125], v[180:181], v[140:141] op_sel_hi:[1,0,1]
	s_nop 0
	v_pk_mul_f32 v[146:147], v[146:147], s[94:95] op_sel_hi:[1,0]
	s_nop 0
	v_exp_f32_e32 v146, v146
	v_exp_f32_e32 v147, v147
	s_nop 0
	v_pk_add_f32 v[146:147], v[146:147], 1.0 op_sel_hi:[1,0]
	s_nop 0
	v_rcp_f32_e32 v181, v146
	v_rcp_f32_e32 v225, v147
	v_add_u32_e32 v146, v224, v161
	v_ashrrev_i32_e32 v147, 31, v146
	v_lshlrev_b64 v[146:147], 15, v[146:147]
	v_lshl_add_u64 v[146:147], s[72:73], 0, v[146:147]
	v_lshl_add_u64 v[208:209], v[146:147], 0, v[198:199]
	v_cvt_pk_bf16_f32 v146, v148, v149
	v_cvt_pk_bf16_f32 v147, v165, v169
	v_cvt_pk_bf16_f32 v148, v173, v177
	v_cvt_pk_bf16_f32 v149, v181, v225
	v_lshl_add_u64 v[250:251], v[208:209], 0, 0
	s_cbranch_vccz .LBB0_645
	global_store_dwordx4 v[208:209], v[146:149], off
	s_mov_b64 s[24:25], 0

.LBB0_1070:
	s_lshl_b32 s0, s92, 8
	v_mov_b32_e32 v225, v210
	v_mov_b32_e32 v222, v213
	s_add_i32 s0, s0, s39
	v_and_b32_e32 v156, 64, v220
	v_add_u32_e32 v182, s0, v222
	v_lshlrev_b32_e32 v130, 2, v225
	v_ashrrev_i32_e32 v131, 31, v130
	v_ashrrev_i32_e32 v183, 31, v182
	v_lshl_add_u64 v[130:131], v[130:131], 2, s[46:47]
	v_lshlrev_b64 v[206:207], 6, v[182:183]
	v_add_u32_e32 v178, 16, v182
	v_lshl_add_u64 v[132:133], v[130:131], 0, v[206:207]
	v_ashrrev_i32_e32 v179, 31, v178
	v_lshl_add_u64 v[250:251], v[132:133], 0, 0
	global_load_dwordx4 v[134:137], v[132:133], off
	v_lshlrev_b64 v[204:205], 6, v[178:179]
	v_add_u32_e32 v174, 32, v182
	v_ashrrev_i32_e32 v175, 31, v174
	s_mov_b32 s98, 0x1000
	s_mov_b32 s99, 0x0
	v_lshl_add_u64 v[252:253], v[250:251], 0, s[98:99]
	global_load_dwordx4 v[138:141], v[252:253], off offset:-3072
	v_lshlrev_b64 v[202:203], 6, v[174:175]
	v_add_u32_e32 v170, 48, v182
	v_ashrrev_i32_e32 v171, 31, v170
	global_load_dwordx4 v[142:145], v[252:253], off offset:-2048
	v_lshlrev_b64 v[200:201], 6, v[170:171]
	v_add_u32_e32 v166, 0x80, v182
	v_ashrrev_i32_e32 v167, 31, v166
	global_load_dwordx4 v[146:149], v[252:253], off offset:-1024
	v_lshlrev_b64 v[198:199], 6, v[166:167]
	v_add_u32_e32 v162, 0x90, v182
	v_ashrrev_i32_e32 v163, 31, v162
	s_mov_b32 s98, 0x3000
	s_mov_b32 s99, 0x0
	v_lshl_add_u64 v[252:253], v[250:251], 0, s[98:99]
	global_load_dwordx4 v[184:187], v[252:253], off offset:-4096
	v_lshlrev_b64 v[192:193], 6, v[162:163]
	v_add_u32_e32 v158, 0xa0, v182
	v_add_u32_e32 v154, 0xb0, v182
	v_ashrrev_i32_e32 v159, 31, v158
	v_ashrrev_i32_e32 v155, 31, v154
	global_load_dwordx4 v[226:229], v[252:253], off offset:-3072
	v_lshlrev_b64 v[190:191], 6, v[158:159]
	v_lshlrev_b64 v[188:189], 6, v[154:155]
	global_load_dwordx4 v[230:233], v[252:253], off offset:-2048
	v_xor_b32_e32 v150, 16, v220
	global_load_dwordx4 v[130:133], v[252:253], off offset:-1024
	s_and_b64 vcc, exec, s[74:75]
	s_cbranch_vccz .LBB0_1072
	s_barrier
.LBB0_1072:
	v_add_u32_e32 v156, 64, v156
	v_cmp_lt_i32_e32 vcc, v150, v156
	s_add_i32 s51, s2, 6
	s_cmp_gt_u32 s2, -7
	v_cndmask_b32_e32 v150, v220, v150, vcc
	v_lshlrev_b32_e32 v223, 2, v150
	v_xor_b32_e32 v150, 32, v220
	v_cmp_lt_i32_e32 vcc, v150, v156
	s_cselect_b32 s0, 2, 3
	s_cselect_b32 s1, -4, -6
	v_cndmask_b32_e32 v150, v220, v150, vcc
	v_lshlrev_b32_e32 v224, 2, v150
	s_cmp_lt_u32 s51, 4
	s_cselect_b32 s0, 1, s0
	s_cselect_b32 s1, -2, s1
	s_cmp_lt_i32 s2, -4
	s_cselect_b32 s33, 0, s0
	s_cselect_b32 s0, 0, s1
	s_add_i32 s0, s0, s51
	s_cmp_lt_i32 s33, 2
	s_waitcnt vmcnt(7)
	v_add_f32_e32 v134, v134, v135
	v_add_f32_e32 v135, v136, v137
	v_add_f32_e32 v134, v134, v135
	ds_bpermute_b32 v135, v223, v134
	s_waitcnt vmcnt(6)
	v_add_f32_e32 v136, v138, v139
	v_add_f32_e32 v137, v140, v141
	v_add_f32_e32 v136, v136, v137
	ds_bpermute_b32 v137, v223, v136
	s_waitcnt lgkmcnt(1)
	v_add_f32_e32 v134, v134, v135
	s_waitcnt vmcnt(5)
	v_add_f32_e32 v138, v142, v143
	v_add_f32_e32 v139, v144, v145
	v_add_f32_e32 v138, v138, v139
	ds_bpermute_b32 v139, v223, v138
	ds_bpermute_b32 v135, v224, v134
	s_waitcnt vmcnt(4)
	v_add_f32_e32 v140, v146, v147
	v_add_f32_e32 v141, v148, v149
	v_add_f32_e32 v140, v140, v141
	ds_bpermute_b32 v141, v223, v140
	s_waitcnt lgkmcnt(3)
	v_add_f32_e32 v136, v136, v137
	s_waitcnt vmcnt(3)
	v_add_f32_e32 v142, v184, v185
	v_add_f32_e32 v143, v186, v187
	v_add_f32_e32 v142, v142, v143
	ds_bpermute_b32 v137, v224, v136
	ds_bpermute_b32 v143, v223, v142
	s_waitcnt lgkmcnt(4)
	v_add_f32_e32 v138, v138, v139
	ds_bpermute_b32 v139, v224, v138
	s_waitcnt vmcnt(2)
	v_add_f32_e32 v144, v226, v227
	v_add_f32_e32 v145, v228, v229
	v_add_f32_e32 v144, v144, v145
	ds_bpermute_b32 v145, v223, v144
	s_waitcnt lgkmcnt(4)
	v_add_f32_e32 v140, v140, v141
	s_waitcnt vmcnt(1)
	v_add_f32_e32 v146, v230, v231
	v_add_f32_e32 v147, v232, v233
	s_waitcnt vmcnt(0)
	v_add_f32_e32 v130, v130, v131
	v_add_f32_e32 v131, v132, v133
	v_add_f32_e32 v146, v146, v147
	v_add_f32_e32 v130, v130, v131
	v_add_f32_e32 v132, v134, v135
	ds_bpermute_b32 v141, v224, v140
	ds_bpermute_b32 v147, v223, v146
	ds_bpermute_b32 v131, v223, v130
	v_fmamk_f32 v132, v132, 0x3a800000, v221
	s_waitcnt lgkmcnt(5)
	v_add_f32_e32 v142, v142, v143
	v_rsq_f32_e32 v184, v132
	v_add_f32_e32 v132, v136, v137
	ds_bpermute_b32 v143, v224, v142
	v_fmamk_f32 v132, v132, 0x3a800000, v221
	s_waitcnt lgkmcnt(4)
	v_add_f32_e32 v144, v144, v145
	v_rsq_f32_e32 v180, v132
	v_add_f32_e32 v132, v138, v139
	ds_bpermute_b32 v145, v224, v144
	v_fmamk_f32 v132, v132, 0x3a800000, v221
	s_waitcnt lgkmcnt(3)
	v_add_f32_e32 v146, v146, v147
	s_waitcnt lgkmcnt(2)
	v_add_f32_e32 v130, v130, v131
	v_rsq_f32_e32 v176, v132
	v_add_f32_e32 v132, v140, v141
	ds_bpermute_b32 v147, v224, v146
	ds_bpermute_b32 v131, v224, v130
	v_fmamk_f32 v132, v132, 0x3a800000, v221
	v_rsq_f32_e32 v172, v132
	s_waitcnt lgkmcnt(3)
	v_add_f32_e32 v132, v142, v143
	v_fmamk_f32 v132, v132, 0x3a800000, v221
	v_rsq_f32_e32 v168, v132
	s_waitcnt lgkmcnt(2)
	v_add_f32_e32 v132, v144, v145
	v_fmamk_f32 v132, v132, 0x3a800000, v221
	v_rsq_f32_e32 v164, v132
	s_waitcnt lgkmcnt(1)
	v_add_f32_e32 v132, v146, v147
	s_waitcnt lgkmcnt(0)
	v_add_f32_e32 v130, v130, v131
	v_fmamk_f32 v132, v132, 0x3a800000, v221
	v_fmamk_f32 v130, v130, 0x3a800000, v221
	v_rsq_f32_e32 v160, v132
	v_rsq_f32_e32 v156, v130
	v_lshl_add_u32 v148, v225, 3, s17
	v_lshl_add_u32 v186, s0, 8, v148
	s_mov_b64 s[0:1], -1
	s_cbranch_scc1 .LBB0_1158
	s_cmp_gt_i32 s33, 2
	s_cbranch_scc0 .LBB0_1139
	s_mov_b32 s95, s26
	s_mov_b32 s91, s24
	s_mov_b32 s90, s17
	s_mov_b64 s[88:89], s[22:23]
	s_mov_b64 s[68:69], s[20:21]
	s_mov_b64 s[66:67], s[18:19]
	s_mov_b32 s53, s16
	v_readlane_b32 s16, v249, 6
	v_ashrrev_i32_e32 v187, 31, v186
	v_readlane_b32 s24, v249, 14
	v_readlane_b32 s25, v249, 15
	v_lshrrev_b32_e32 v147, 3, v182
	v_lshlrev_b32_e32 v146, 1, v148
	v_lshl_add_u64 v[134:135], v[186:187], 2, s[24:25]
	s_mov_b32 s98, 0x10
	s_mov_b32 s99, 0x0
	v_lshl_add_u64 v[250:251], v[134:135], 0, s[98:99]
	global_load_dwordx4 v[138:141], v[134:135], off offset:16
	s_mov_b32 s98, 0xfffff000
	s_mov_b32 s99, 0xffffffff
	v_lshl_add_u64 v[252:253], v[250:251], 0, s[98:99]
	global_load_dwordx4 v[142:145], v[252:253], off offset:4080
	s_mov_b32 s98, 0x1000
	s_mov_b32 s99, 0x0
	v_lshl_add_u64 v[252:253], v[250:251], 0, s[98:99]
	global_load_dwordx4 v[130:133], v[252:253], off offset:-3584
	s_nop 0
	global_load_dwordx4 v[134:137], v[252:253], off offset:-3600
	v_bfe_u32 v187, v148, 5, 1
	v_and_or_b32 v147, v147, 14, v187
	v_and_b32_e32 v157, 48, v146
	v_ashrrev_i32_e32 v146, 3, v182
	v_lshlrev_b32_e32 v148, 6, v182
	v_lshlrev_b32_e32 v161, 10, v147
	v_lshlrev_b32_e32 v147, 2, v182
	v_and_b32_e32 v165, 0xffffffe0, v146
	v_lshlrev_b32_e32 v146, 7, v182
	v_and_b32_e32 v148, 0x3c0, v148
	v_and_b32_e32 v147, 32, v147
	v_and_b32_e32 v146, 0x4000, v146
	v_bitop3_b32 v147, v157, v147, v148 bitop3:0x36
	v_or3_b32 v150, v146, v147, v161
	v_ashrrev_i32_e32 v226, 6, v186
	s_cmpk_lt_i32 s92, 0x80
	s_cselect_b64 s[0:1], -1, 0
	s_xor_b64 s[62:63], s[36:37], -1
	s_and_b64 s[62:63], s[62:63], s[0:1]
	s_mov_b64 s[64:65], -1
	s_and_b64 vcc, exec, s[62:63]
	v_readlane_b32 s17, v249, 7
	v_readlane_b32 s18, v249, 8
	v_readlane_b32 s19, v249, 9
	v_readlane_b32 s20, v249, 10
	v_readlane_b32 s21, v249, 11
	v_readlane_b32 s22, v249, 12
	v_readlane_b32 s23, v249, 13
	v_readlane_b32 s26, v249, 16
	v_readlane_b32 s27, v249, 17
	v_readlane_b32 s28, v249, 18
	v_readlane_b32 s29, v249, 19
	v_readlane_b32 s30, v249, 20
	v_readlane_b32 s31, v249, 21
	s_waitcnt vmcnt(2)
	v_pk_fma_f32 v[146:147], v[126:127], v[184:185], v[142:143] op_sel_hi:[1,0,1]
	s_nop 0
	v_pk_mul_f32 v[146:147], v[146:147], s[38:39] op_sel_hi:[1,0]
	s_nop 0
	v_exp_f32_e32 v146, v146
	v_exp_f32_e32 v147, v147
	s_nop 0
	v_pk_add_f32 v[146:147], v[146:147], 1.0 op_sel_hi:[1,0]
	s_nop 0
	v_rcp_f32_e32 v148, v146
	v_rcp_f32_e32 v149, v147
	v_pk_fma_f32 v[146:147], v[128:129], v[184:185], v[144:145] op_sel_hi:[1,0,1]
	s_nop 0
	v_pk_mul_f32 v[146:147], v[146:147], s[38:39] op_sel_hi:[1,0]
	s_nop 0
	v_exp_f32_e32 v146, v146
	v_exp_f32_e32 v147, v147
	s_nop 0
	v_pk_add_f32 v[146:147], v[146:147], 1.0 op_sel_hi:[1,0]
	s_nop 0
	v_rcp_f32_e32 v169, v146
	v_rcp_f32_e32 v173, v147
	v_pk_fma_f32 v[146:147], v[122:123], v[184:185], v[138:139] op_sel_hi:[1,0,1]
	s_nop 0
	v_pk_mul_f32 v[146:147], v[146:147], s[38:39] op_sel_hi:[1,0]
	s_nop 0
	v_exp_f32_e32 v146, v146
	v_exp_f32_e32 v147, v147
	s_nop 0
	v_pk_add_f32 v[146:147], v[146:147], 1.0 op_sel_hi:[1,0]
	s_nop 0
	v_rcp_f32_e32 v177, v146
	v_rcp_f32_e32 v181, v147
	v_pk_fma_f32 v[146:147], v[124:125], v[184:185], v[140:141] op_sel_hi:[1,0,1]
	s_nop 0
	v_pk_mul_f32 v[146:147], v[146:147], s[38:39] op_sel_hi:[1,0]
	s_nop 0
	v_exp_f32_e32 v146, v146
	v_exp_f32_e32 v147, v147
	s_nop 0
	v_pk_add_f32 v[146:147], v[146:147], 1.0 op_sel_hi:[1,0]
	s_nop 0
	v_rcp_f32_e32 v185, v146
	v_rcp_f32_e32 v227, v147
	v_add_u32_e32 v146, v226, v165
	v_ashrrev_i32_e32 v147, 31, v146
	v_lshlrev_b64 v[146:147], 15, v[146:147]
	v_lshl_add_u64 v[146:147], s[80:81], 0, v[146:147]
	v_lshl_add_u64 v[208:209], v[146:147], 0, v[150:151]
	v_cvt_pk_bf16_f32 v146, v148, v149
	v_cvt_pk_bf16_f32 v147, v169, v173
	v_cvt_pk_bf16_f32 v148, v177, v181
	v_cvt_pk_bf16_f32 v149, v185, v227
	v_lshl_add_u64 v[250:251], v[208:209], 0, 0
	s_cbranch_vccz .LBB0_1076
	global_store_dwordx4 v[208:209], v[146:149], off
	s_mov_b64 s[64:65], 0

.LBB0_1716:
	v_mov_b32_e32 v130, v204
	v_mov_b32_e32 v178, v210
	s_lshl_b32 s13, s73, 8
	s_add_i32 s13, s13, s61
	v_add_u32_e32 v144, s13, v130
	v_lshlrev_b32_e32 v130, 2, v178
	v_ashrrev_i32_e32 v131, 31, v130
	v_ashrrev_i32_e32 v145, 31, v144
	v_lshl_add_u64 v[174:175], v[130:131], 2, s[2:3]
	v_lshlrev_b64 v[130:131], 6, v[144:145]
	v_lshl_add_u64 v[130:131], v[174:175], 0, v[130:131]
	v_add_u32_e32 v138, 48, v144
	v_lshl_add_u64 v[180:181], v[130:131], 0, 0
	global_load_dwordx4 v[146:149], v[130:131], off
	s_mov_b32 s98, 0x1000
	s_mov_b32 s99, 0x0
	v_lshl_add_u64 v[182:183], v[180:181], 0, s[98:99]
	global_load_dwordx4 v[150:153], v[182:183], off offset:-3072
	v_ashrrev_i32_e32 v139, 31, v138
	global_load_dwordx4 v[154:157], v[182:183], off offset:-2048
	global_load_dwordx4 v[158:161], v[182:183], off offset:-1024
	s_mov_b32 s98, 0x3000
	s_mov_b32 s99, 0x0
	v_lshl_add_u64 v[182:183], v[180:181], 0, s[98:99]
	global_load_dwordx4 v[162:165], v[182:183], off offset:-4096
	global_load_dwordx4 v[166:169], v[182:183], off offset:-3072
	v_add_u32_e32 v132, 0xa0, v144
	global_load_dwordx4 v[170:173], v[182:183], off offset:-2048
	v_add_u32_e32 v130, 0xb0, v144
	global_load_dwordx4 v[174:177], v[182:183], off offset:-1024
	s_and_b64 vcc, exec, s[22:23]
	s_cbranch_vccz .LBB0_1718
	s_barrier
.LBB0_1718:
	s_lshl_b32 s13, s10, 8
	v_and_b32_e32 v133, 64, v206
	v_xor_b32_e32 v135, 16, v206
	s_or_b32 s13, s13, s63
	v_add_u32_e32 v133, 64, v133
	v_lshl_add_u32 v137, v178, 3, s13
	v_cmp_lt_i32_e32 vcc, v135, v133
	v_xor_b32_e32 v131, 32, v206
	s_waitcnt vmcnt(7)
	v_mov_b32_e32 v178, v147
	v_mov_b32_e32 v179, v148
	v_mov_b32_e32 v147, v149
	v_cndmask_b32_e32 v135, v206, v135, vcc
	v_pk_add_f32 v[146:147], v[178:179], v[146:147]
	s_waitcnt vmcnt(6)
	v_mov_b32_e32 v148, v151
	v_mov_b32_e32 v149, v152
	v_mov_b32_e32 v151, v153
	s_waitcnt vmcnt(5)
	v_mov_b32_e32 v152, v155
	v_mov_b32_e32 v153, v156
	v_mov_b32_e32 v155, v157
	v_cmp_lt_i32_e32 vcc, v131, v133
	v_lshlrev_b32_e32 v133, 2, v135
	v_add_f32_e32 v135, v146, v147
	v_pk_add_f32 v[146:147], v[148:149], v[150:151]
	v_pk_add_f32 v[148:149], v[152:153], v[154:155]
	v_add_f32_e32 v141, v146, v147
	v_add_f32_e32 v143, v148, v149
	ds_bpermute_b32 v139, v133, v135
	ds_bpermute_b32 v146, v133, v141
	ds_bpermute_b32 v147, v133, v143
	v_cndmask_b32_e32 v131, v206, v131, vcc
	s_waitcnt vmcnt(4)
	v_mov_b32_e32 v156, v159
	v_mov_b32_e32 v157, v160
	v_mov_b32_e32 v159, v161
	v_lshlrev_b32_e32 v131, 2, v131
	v_pk_add_f32 v[150:151], v[156:157], v[158:159]
	s_waitcnt lgkmcnt(2)
	v_add_f32_e32 v135, v135, v139
	s_waitcnt lgkmcnt(1)
	v_add_f32_e32 v141, v141, v146
	s_waitcnt lgkmcnt(0)
	v_add_f32_e32 v143, v143, v147
	v_add_f32_e32 v145, v150, v151
	ds_bpermute_b32 v139, v131, v135
	ds_bpermute_b32 v146, v131, v141
	ds_bpermute_b32 v147, v131, v143
	ds_bpermute_b32 v148, v133, v145
	s_waitcnt vmcnt(3)
	v_mov_b32_e32 v160, v163
	v_mov_b32_e32 v161, v164
	v_mov_b32_e32 v163, v165
	v_pk_add_f32 v[152:153], v[160:161], v[162:163]
	s_waitcnt lgkmcnt(3)
	v_add_f32_e32 v135, v135, v139
	s_waitcnt lgkmcnt(2)
	v_add_f32_e32 v139, v141, v146
	s_waitcnt lgkmcnt(1)
	v_add_f32_e32 v141, v143, v147
	v_add_f32_e32 v143, v152, v153
	s_waitcnt lgkmcnt(0)
	v_add_f32_e32 v145, v145, v148
	ds_bpermute_b32 v146, v133, v143
	ds_bpermute_b32 v148, v131, v145
	s_waitcnt vmcnt(2)
	v_mov_b32_e32 v147, v168
	v_fmamk_f32 v135, v135, 0x3a800000, v207
	v_rsq_f32_e32 v135, v135
	s_waitcnt lgkmcnt(1)
	v_add_f32_e32 v143, v143, v146
	v_mov_b32_e32 v146, v167
	v_mov_b32_e32 v167, v169
	s_waitcnt lgkmcnt(0)
	v_add_f32_e32 v145, v145, v148
	ds_bpermute_b32 v148, v131, v143
	v_pk_add_f32 v[146:147], v[146:147], v[166:167]
	v_fmamk_f32 v145, v145, 0x3a800000, v207
	v_add_f32_e32 v146, v146, v147
	ds_bpermute_b32 v147, v133, v146
	s_waitcnt lgkmcnt(1)
	v_add_f32_e32 v143, v143, v148
	v_fmamk_f32 v143, v143, 0x3a800000, v207
	v_rsq_f32_e32 v155, v143
	v_rsq_f32_e32 v154, v145
	s_waitcnt lgkmcnt(0)
	v_add_f32_e32 v143, v146, v147
	s_waitcnt vmcnt(1)
	v_mov_b32_e32 v146, v171
	v_mov_b32_e32 v147, v172
	v_mov_b32_e32 v171, v173
	v_pk_add_f32 v[146:147], v[146:147], v[170:171]
	ds_bpermute_b32 v145, v131, v143
	v_add_f32_e32 v148, v146, v147
	ds_bpermute_b32 v149, v133, v148
	s_waitcnt vmcnt(0)
	v_mov_b32_e32 v146, v175
	v_mov_b32_e32 v147, v176
	v_mov_b32_e32 v175, v177
	v_pk_add_f32 v[146:147], v[146:147], v[174:175]
	s_waitcnt lgkmcnt(1)
	v_add_f32_e32 v143, v143, v145
	v_add_f32_e32 v146, v146, v147
	ds_bpermute_b32 v133, v133, v146
	s_waitcnt lgkmcnt(1)
	v_add_f32_e32 v145, v148, v149
	ds_bpermute_b32 v147, v131, v145
	v_fmamk_f32 v143, v143, 0x3a800000, v207
	v_rsq_f32_e32 v156, v143
	s_waitcnt lgkmcnt(1)
	v_add_f32_e32 v133, v146, v133
	ds_bpermute_b32 v131, v131, v133
	s_waitcnt lgkmcnt(1)
	v_add_f32_e32 v143, v145, v147
	v_fmamk_f32 v143, v143, 0x3a800000, v207
	v_rsq_f32_e32 v157, v143
	v_bfe_u32 v158, v137, 5, 1
	v_lshrrev_b32_e32 v143, 3, v144
	v_and_or_b32 v143, v143, 14, v158
	s_waitcnt lgkmcnt(0)
	v_add_f32_e32 v131, v133, v131
	v_lshlrev_b32_e32 v133, 1, v137
	v_lshlrev_b32_e32 v145, 6, v144
	v_lshlrev_b32_e32 v160, 10, v143
	v_lshlrev_b32_e32 v143, 2, v144
	v_and_b32_e32 v159, 48, v133
	v_mul_f32_e32 v148, 0x3db8aa3b, v135
	v_and_b32_e32 v145, 0x3c0, v145
	v_and_b32_e32 v143, 32, v143
	v_ashrrev_i32_e32 v133, 4, v144
	v_lshlrev_b32_e32 v135, 7, v144
	v_bitop3_b32 v143, v159, v143, v145 bitop3:0x36
	v_pk_mul_f32 v[146:147], v[128:129], v[148:149] op_sel_hi:[1,0]
	v_pk_mul_f32 v[144:145], v[126:127], v[148:149] op_sel_hi:[1,0]
	v_pk_mul_f32 v[152:153], v[122:123], v[148:149] op_sel_hi:[1,0]
	v_and_b32_e32 v133, -16, v133
	v_pk_mul_f32 v[150:151], v[124:125], v[148:149] op_sel_hi:[1,0]
	v_cvt_pk_bf16_f32 v144, v144, v145
	v_cvt_pk_bf16_f32 v145, v146, v147
	v_cvt_pk_bf16_f32 v146, v152, v153
	v_ashrrev_i32_e32 v152, 6, v137
	v_cvt_pk_bf16_f32 v147, v150, v151
	v_add_u32_e32 v150, v152, v133
	v_ashrrev_i32_e32 v151, 31, v150
	v_and_b32_e32 v135, 0x4000, v135
	v_lshlrev_b64 v[150:151], 15, v[150:151]
	v_or3_b32 v198, v135, v143, v160
	v_lshl_add_u64 v[150:151], s[20:21], 0, v[150:151]
	v_lshl_add_u64 v[150:151], v[150:151], 0, v[198:199]
	v_add_u32_e32 v135, 0x80, v137
	v_lshl_add_u64 v[180:181], v[150:151], 0, 0
	global_store_dwordx4 v[150:151], v[144:147], off
	v_pk_mul_f32 v[150:151], v[92:93], v[148:149] op_sel_hi:[1,0]
	v_ashrrev_i32_e32 v153, 6, v135
	v_pk_mul_f32 v[146:147], v[96:97], v[148:149] op_sel_hi:[1,0]
	v_pk_mul_f32 v[144:145], v[94:95], v[148:149] op_sel_hi:[1,0]
	v_pk_mul_f32 v[148:149], v[90:91], v[148:149] op_sel_hi:[1,0]
	v_fmamk_f32 v139, v139, 0x3a800000, v207
	v_cvt_pk_bf16_f32 v144, v144, v145
	v_cvt_pk_bf16_f32 v145, v146, v147
	v_cvt_pk_bf16_f32 v146, v148, v149
	v_rsq_f32_e32 v139, v139
	s_nop 0
	s_nop 0
	s_nop 0
	v_cvt_pk_bf16_f32 v147, v150, v151
	s_nop 0
	s_mov_b32 s98, 0x11000
	s_mov_b32 s99, 0x0
	v_lshl_add_u64 v[182:183], v[180:181], 0, s[98:99]
	global_store_dwordx4 v[182:183], v[144:147], off offset:-4096
	s_nop 0
	s_nop 0
	v_mul_f32_e32 v146, 0x3db8aa3b, v139
	s_nop 0
	s_nop 0
	v_pk_mul_f32 v[144:145], v[120:121], v[146:147] op_sel_hi:[1,0]
	v_pk_mul_f32 v[142:143], v[118:119], v[146:147] op_sel_hi:[1,0]
	v_pk_mul_f32 v[148:149], v[116:117], v[146:147] op_sel_hi:[1,0]
	v_cvt_pk_bf16_f32 v142, v142, v143
	v_cvt_pk_bf16_f32 v143, v144, v145
	v_cvt_pk_bf16_f32 v145, v148, v149
	v_pk_mul_f32 v[150:151], v[114:115], v[146:147] op_sel_hi:[1,0]
	v_cvt_pk_bf16_f32 v144, v150, v151
	s_mov_b32 s98, 0x1000
	s_mov_b32 s99, 0x0
	v_lshl_add_u64 v[184:185], v[180:181], 0, s[98:99]
	global_store_dwordx4 v[184:185], v[142:145], off offset:-2048
	v_pk_mul_f32 v[148:149], v[84:85], v[146:147] op_sel_hi:[1,0]
	v_fmamk_f32 v141, v141, 0x3a800000, v207
	v_pk_mul_f32 v[144:145], v[88:89], v[146:147] op_sel_hi:[1,0]
	v_pk_mul_f32 v[142:143], v[86:87], v[146:147] op_sel_hi:[1,0]
	v_pk_mul_f32 v[146:147], v[82:83], v[146:147] op_sel_hi:[1,0]
	v_cvt_pk_bf16_f32 v142, v142, v143
	v_cvt_pk_bf16_f32 v143, v144, v145
	v_cvt_pk_bf16_f32 v144, v146, v147
	v_rsq_f32_e32 v141, v141
	s_nop 0
	s_nop 0
	s_nop 0
	v_cvt_pk_bf16_f32 v145, v148, v149
	s_nop 0
	global_store_dwordx4 v[182:183], v[142:145], off offset:-2048
	s_nop 0
	s_nop 0
	v_mul_f32_e32 v144, 0x3db8aa3b, v141
	s_nop 0
	s_nop 0
	v_pk_mul_f32 v[142:143], v[112:113], v[144:145] op_sel_hi:[1,0]
	v_pk_mul_f32 v[140:141], v[110:111], v[144:145] op_sel_hi:[1,0]
	v_pk_mul_f32 v[146:147], v[108:109], v[144:145] op_sel_hi:[1,0]
	v_cvt_pk_bf16_f32 v140, v140, v141
	v_cvt_pk_bf16_f32 v141, v142, v143
	v_cvt_pk_bf16_f32 v143, v146, v147
	v_pk_mul_f32 v[148:149], v[106:107], v[144:145] op_sel_hi:[1,0]
	v_cvt_pk_bf16_f32 v142, v148, v149
	global_store_dwordx4 v[184:185], v[140:143], off
	v_pk_mul_f32 v[146:147], v[76:77], v[144:145] op_sel_hi:[1,0]
	s_nop 0
	v_pk_mul_f32 v[142:143], v[80:81], v[144:145] op_sel_hi:[1,0]
	v_pk_mul_f32 v[140:141], v[78:79], v[144:145] op_sel_hi:[1,0]
	v_pk_mul_f32 v[144:145], v[74:75], v[144:145] op_sel_hi:[1,0]
	v_cvt_pk_bf16_f32 v140, v140, v141
	v_cvt_pk_bf16_f32 v141, v142, v143
	v_cvt_pk_bf16_f32 v142, v144, v145
	v_cvt_pk_bf16_f32 v143, v146, v147
	global_store_dwordx4 v[182:183], v[140:143], off
	s_nop 0
	s_nop 0
	v_mul_f32_e32 v142, 0x3db8aa3b, v154
	s_nop 0
	s_nop 0
	v_pk_mul_f32 v[140:141], v[104:105], v[142:143] op_sel_hi:[1,0]
	v_pk_mul_f32 v[138:139], v[102:103], v[142:143] op_sel_hi:[1,0]
	v_pk_mul_f32 v[144:145], v[100:101], v[142:143] op_sel_hi:[1,0]
	v_cvt_pk_bf16_f32 v138, v138, v139
	v_cvt_pk_bf16_f32 v139, v140, v141
	v_cvt_pk_bf16_f32 v141, v144, v145
	v_pk_mul_f32 v[146:147], v[98:99], v[142:143] op_sel_hi:[1,0]
	v_cvt_pk_bf16_f32 v140, v146, v147
	global_store_dwordx4 v[184:185], v[138:141], off offset:2048
	v_pk_mul_f32 v[144:145], v[68:69], v[142:143] op_sel_hi:[1,0]
	s_nop 0
	v_pk_mul_f32 v[140:141], v[72:73], v[142:143] op_sel_hi:[1,0]
	v_pk_mul_f32 v[138:139], v[70:71], v[142:143] op_sel_hi:[1,0]
	v_pk_mul_f32 v[142:143], v[66:67], v[142:143] op_sel_hi:[1,0]
	v_cvt_pk_bf16_f32 v138, v138, v139
	v_cvt_pk_bf16_f32 v139, v140, v141
	v_cvt_pk_bf16_f32 v140, v142, v143
	v_cvt_pk_bf16_f32 v141, v144, v145
	global_store_dwordx4 v[182:183], v[138:141], off offset:2048
	s_nop 0
	s_nop 0
	v_mul_f32_e32 v140, 0x3db8aa3b, v155
	s_nop 0
	s_nop 0
	v_pk_mul_f32 v[138:139], v[64:65], v[140:141] op_sel_hi:[1,0]
	v_pk_mul_f32 v[136:137], v[62:63], v[140:141] op_sel_hi:[1,0]
	v_pk_mul_f32 v[142:143], v[60:61], v[140:141] op_sel_hi:[1,0]
	v_cvt_pk_bf16_f32 v136, v136, v137
	v_cvt_pk_bf16_f32 v137, v138, v139
	v_cvt_pk_bf16_f32 v139, v142, v143
	v_pk_mul_f32 v[144:145], v[58:59], v[140:141] op_sel_hi:[1,0]
	v_cvt_pk_bf16_f32 v138, v144, v145
	s_mov_b32 s98, 0x5000
	s_mov_b32 s99, 0x0
	v_lshl_add_u64 v[182:183], v[180:181], 0, s[98:99]
	global_store_dwordx4 v[182:183], v[136:139], off offset:-4096
	v_pk_mul_f32 v[142:143], v[28:29], v[140:141] op_sel_hi:[1,0]
	s_nop 0
	v_pk_mul_f32 v[138:139], v[32:33], v[140:141] op_sel_hi:[1,0]
	v_pk_mul_f32 v[136:137], v[30:31], v[140:141] op_sel_hi:[1,0]
	v_pk_mul_f32 v[140:141], v[26:27], v[140:141] op_sel_hi:[1,0]
	v_cvt_pk_bf16_f32 v136, v136, v137
	v_cvt_pk_bf16_f32 v137, v138, v139
	v_cvt_pk_bf16_f32 v138, v140, v141
	v_cvt_pk_bf16_f32 v139, v142, v143
	s_mov_b32 s98, 0x15000
	s_mov_b32 s99, 0x0
	v_lshl_add_u64 v[184:185], v[180:181], 0, s[98:99]
	global_store_dwordx4 v[184:185], v[136:139], off offset:-4096
	s_nop 0
	s_nop 0
	s_nop 0
	s_nop 0
	s_nop 0
	v_mul_f32_e32 v138, 0x3db8aa3b, v156
	v_pk_mul_f32 v[136:137], v[56:57], v[138:139] op_sel_hi:[1,0]
	v_pk_mul_f32 v[134:135], v[54:55], v[138:139] op_sel_hi:[1,0]
	v_pk_mul_f32 v[140:141], v[52:53], v[138:139] op_sel_hi:[1,0]
	v_cvt_pk_bf16_f32 v134, v134, v135
	v_cvt_pk_bf16_f32 v135, v136, v137
	v_cvt_pk_bf16_f32 v137, v140, v141
	v_pk_mul_f32 v[142:143], v[50:51], v[138:139] op_sel_hi:[1,0]
	v_cvt_pk_bf16_f32 v136, v142, v143
	global_store_dwordx4 v[182:183], v[134:137], off offset:-2048
	v_pk_mul_f32 v[140:141], v[20:21], v[138:139] op_sel_hi:[1,0]
	v_fmamk_f32 v131, v131, 0x3a800000, v207
	v_pk_mul_f32 v[136:137], v[24:25], v[138:139] op_sel_hi:[1,0]
	v_pk_mul_f32 v[134:135], v[22:23], v[138:139] op_sel_hi:[1,0]
	v_pk_mul_f32 v[138:139], v[18:19], v[138:139] op_sel_hi:[1,0]
	v_cvt_pk_bf16_f32 v134, v134, v135
	v_cvt_pk_bf16_f32 v135, v136, v137
	v_cvt_pk_bf16_f32 v136, v138, v139
	v_cvt_pk_bf16_f32 v137, v140, v141
	v_ashrrev_i32_e32 v133, 4, v132
	global_store_dwordx4 v[184:185], v[134:137], off offset:-2048
	v_and_b32_e32 v142, -16, v133
	s_nop 0
	s_nop 0
	s_nop 0
	s_nop 0
	v_mul_f32_e32 v136, 0x3db8aa3b, v157
	v_pk_mul_f32 v[134:135], v[48:49], v[136:137] op_sel_hi:[1,0]
	v_pk_mul_f32 v[132:133], v[46:47], v[136:137] op_sel_hi:[1,0]
	v_pk_mul_f32 v[138:139], v[44:45], v[136:137] op_sel_hi:[1,0]
	v_cvt_pk_bf16_f32 v132, v132, v133
	v_cvt_pk_bf16_f32 v133, v134, v135
	v_cvt_pk_bf16_f32 v135, v138, v139
	v_pk_mul_f32 v[140:141], v[42:43], v[136:137] op_sel_hi:[1,0]
	v_cvt_pk_bf16_f32 v134, v140, v141
	global_store_dwordx4 v[182:183], v[132:135], off
	v_pk_mul_f32 v[138:139], v[12:13], v[136:137] op_sel_hi:[1,0]
	v_rsq_f32_e32 v131, v131
	v_pk_mul_f32 v[134:135], v[16:17], v[136:137] op_sel_hi:[1,0]
	v_pk_mul_f32 v[132:133], v[14:15], v[136:137] op_sel_hi:[1,0]
	v_pk_mul_f32 v[136:137], v[10:11], v[136:137] op_sel_hi:[1,0]
	v_cvt_pk_bf16_f32 v132, v132, v133
	v_cvt_pk_bf16_f32 v133, v134, v135
	v_cvt_pk_bf16_f32 v134, v136, v137
	v_cvt_pk_bf16_f32 v135, v138, v139
	global_store_dwordx4 v[184:185], v[132:135], off
	s_andn2_b64 vcc, exec, s[40:41]
	s_nop 0
	v_mul_f32_e32 v134, 0x3db8aa3b, v131
	v_ashrrev_i32_e32 v131, 4, v130
	v_and_b32_e32 v140, -16, v131
	v_lshlrev_b32_e32 v131, 7, v130
	v_lshrrev_b32_e32 v132, 3, v130
	v_lshlrev_b32_e32 v133, 6, v130
	v_lshlrev_b32_e32 v130, 2, v130
	v_and_or_b32 v132, v132, 14, v158
	v_and_b32_e32 v133, 0x3c0, v133
	v_and_b32_e32 v130, 32, v130
	v_and_b32_e32 v131, 0x4000, v131
	v_lshlrev_b32_e32 v132, 10, v132
	v_bitop3_b32 v130, v133, v130, v159 bitop3:0x36
	v_or3_b32 v198, v132, v131, v130
	v_pk_mul_f32 v[132:133], v[40:41], v[134:135] op_sel_hi:[1,0]
	v_pk_mul_f32 v[130:131], v[38:39], v[134:135] op_sel_hi:[1,0]
	v_pk_mul_f32 v[136:137], v[36:37], v[134:135] op_sel_hi:[1,0]
	v_cvt_pk_bf16_f32 v130, v130, v131
	v_cvt_pk_bf16_f32 v131, v132, v133
	v_cvt_pk_bf16_f32 v133, v136, v137
	v_pk_mul_f32 v[138:139], v[34:35], v[134:135] op_sel_hi:[1,0]
	v_cvt_pk_bf16_f32 v132, v138, v139
	global_store_dwordx4 v[182:183], v[130:133], off offset:2048
	v_pk_mul_f32 v[136:137], v[4:5], v[134:135] op_sel_hi:[1,0]
	s_nop 0
	v_pk_mul_f32 v[132:133], v[8:9], v[134:135] op_sel_hi:[1,0]
	v_pk_mul_f32 v[130:131], v[6:7], v[134:135] op_sel_hi:[1,0]
	v_pk_mul_f32 v[134:135], v[2:3], v[134:135] op_sel_hi:[1,0]
	v_cvt_pk_bf16_f32 v130, v130, v131
	v_cvt_pk_bf16_f32 v131, v132, v133
	v_cvt_pk_bf16_f32 v132, v134, v135
	v_add_u32_e32 v134, v153, v140
	v_ashrrev_i32_e32 v135, 31, v134
	v_lshlrev_b64 v[134:135], 15, v[134:135]
	v_lshl_add_u64 v[134:135], s[20:21], 0, v[134:135]
	v_cvt_pk_bf16_f32 v133, v136, v137
	v_lshl_add_u64 v[134:135], v[134:135], 0, v[198:199]
	global_store_dwordx4 v[184:185], v[130:133], off offset:2048
	s_cbranch_vccnz .LBB0_1679
	s_andn2_b64 vcc, exec, s[18:19]
	s_cbranch_vccnz .LBB0_1678
	s_barrier
	s_branch .LBB0_1678

.LBB0_2124:
	v_mov_b32_e32 v137, v210
	v_mov_b32_e32 v130, v202
	v_xor_b32_e32 v138, 32, v204
	v_add_u32_e32 v136, s68, v130
	v_lshl_add_u32 v130, s82, 8, v136
	v_lshlrev_b32_e32 v132, 2, v137
	v_ashrrev_i32_e32 v133, 31, v132
	v_ashrrev_i32_e32 v131, 31, v130
	v_lshl_add_u64 v[132:133], v[132:133], 2, s[2:3]
	v_lshlrev_b64 v[130:131], 6, v[130:131]
	v_lshl_add_u64 v[134:135], v[132:133], 0, v[130:131]
	v_lshl_add_u64 v[170:171], v[134:135], 0, 0
	global_load_dwordx4 v[130:133], v[134:135], off
	s_mov_b32 s98, 0x1000
	s_mov_b32 s99, 0x0
	v_lshl_add_u64 v[172:173], v[170:171], 0, s[98:99]
	global_load_dwordx4 v[140:143], v[172:173], off offset:-3072
	global_load_dwordx4 v[144:147], v[172:173], off offset:-2048
	global_load_dwordx4 v[148:151], v[172:173], off offset:-1024
	v_add_co_u32_e32 v134, vcc, s13, v134
	s_mul_i32 s10, s82, 44
	s_nop 0
	v_addc_co_u32_e32 v135, vcc, 0, v135, vcc
	global_load_dwordx4 v[152:155], v[134:135], off
	global_load_dwordx4 v[156:159], v[134:135], off offset:1024
	global_load_dwordx4 v[160:163], v[134:135], off offset:2048
	global_load_dwordx4 v[164:167], v[134:135], off offset:3072
	s_and_b64 vcc, exec, s[24:25]
	s_cbranch_vccz .LBB0_2126
	s_barrier
.LBB0_2126:
	v_and_b32_e32 v135, 64, v204
	v_xor_b32_e32 v134, 16, v204
	v_add_u32_e32 v135, 64, v135
	v_cmp_lt_i32_e32 vcc, v134, v135
	s_lshl_b32 s11, s12, 1
	s_add_i32 s10, s10, s11
	v_cndmask_b32_e32 v134, v204, v134, vcc
	v_cmp_lt_i32_e32 vcc, v138, v135
	v_lshlrev_b32_e32 v139, 2, v134
	s_or_b32 s10, s10, s74
	v_cndmask_b32_e32 v135, v204, v138, vcc
	v_lshlrev_b32_e32 v168, 2, v135
	s_ashr_i32 s11, s10, 31
	v_lshl_add_u32 v138, v137, 3, s75
	s_lshl_b64 s[10:11], s[10:11], 15
	v_lshlrev_b32_e32 v137, 4, v137
	v_ashrrev_i32_e32 v138, 5, v138
	s_add_u32 s50, s65, s10
	v_and_b32_e32 v137, 48, v137
	s_addc_u32 s51, s66, s11
	s_cmpk_lt_i32 s82, 0x80
	s_cselect_b64 s[52:53], -1, 0
	s_xor_b64 s[54:55], s[36:37], -1
	s_and_b64 s[52:53], s[54:55], s[52:53]
	s_mov_b64 s[10:11], -1
	s_and_b64 vcc, exec, s[52:53]
	s_waitcnt vmcnt(7)
	v_mov_b32_e32 v134, v131
	v_mov_b32_e32 v135, v132
	v_mov_b32_e32 v131, v133
	s_waitcnt vmcnt(6)
	v_add_f32_e32 v132, v140, v141
	v_add_f32_e32 v133, v142, v143
	s_waitcnt vmcnt(5)
	v_add_f32_e32 v140, v144, v145
	v_add_f32_e32 v141, v146, v147
	s_waitcnt vmcnt(4)
	v_add_f32_e32 v142, v148, v149
	v_add_f32_e32 v143, v150, v151
	v_pk_add_f32 v[130:131], v[134:135], v[130:131]
	v_add_f32_e32 v132, v132, v133
	v_add_f32_e32 v133, v140, v141
	v_add_f32_e32 v134, v142, v143
	s_waitcnt vmcnt(3)
	v_add_f32_e32 v135, v152, v153
	v_add_f32_e32 v140, v154, v155
	s_waitcnt vmcnt(2)
	v_add_f32_e32 v141, v156, v157
	v_add_f32_e32 v142, v158, v159
	s_waitcnt vmcnt(1)
	v_add_f32_e32 v143, v160, v161
	v_add_f32_e32 v144, v162, v163
	v_add_f32_e32 v130, v130, v131
	v_add_f32_e32 v135, v135, v140
	v_add_f32_e32 v140, v141, v142
	v_add_f32_e32 v141, v143, v144
	ds_bpermute_b32 v143, v139, v130
	ds_bpermute_b32 v131, v139, v132
	ds_bpermute_b32 v148, v139, v134
	ds_bpermute_b32 v144, v139, v135
	ds_bpermute_b32 v147, v139, v133
	s_waitcnt lgkmcnt(4)
	v_add_f32_e32 v130, v130, v143
	s_waitcnt lgkmcnt(3)
	v_add_f32_e32 v152, v132, v131
	ds_bpermute_b32 v131, v168, v130
	ds_bpermute_b32 v154, v139, v141
	s_waitcnt vmcnt(0)
	v_add_f32_e32 v145, v164, v165
	v_add_f32_e32 v146, v166, v167
	v_add_f32_e32 v142, v145, v146
	s_waitcnt lgkmcnt(1)
	v_add_f32_e32 v130, v130, v131
	v_fmamk_f32 v130, v130, 0x3a800000, v205
	v_rsq_f32_e32 v130, v130
	v_add_f32_e32 v148, v134, v148
	v_add_f32_e32 v145, v135, v144
	v_add_f32_e32 v150, v133, v147
	v_pk_mul_f32 v[134:135], v[128:129], v[130:131] op_sel_hi:[1,0]
	v_pk_mul_f32 v[132:133], v[126:127], v[130:131] op_sel_hi:[1,0]
	v_pk_mul_f32 v[156:157], v[134:135], s[30:31] op_sel_hi:[1,0]
	s_waitcnt lgkmcnt(0)
	v_add_f32_e32 v141, v141, v154
	v_pk_mul_f32 v[154:155], v[132:133], s[30:31] op_sel_hi:[1,0]
	v_exp_f32_e32 v156, v156
	v_exp_f32_e32 v157, v157
	v_exp_f32_e32 v154, v154
	v_exp_f32_e32 v155, v155
	v_pk_mul_f32 v[160:161], v[96:97], v[130:131] op_sel_hi:[1,0]
	v_pk_add_f32 v[156:157], v[156:157], 1.0 op_sel_hi:[1,0]
	v_pk_mul_f32 v[162:163], v[122:123], v[130:131] op_sel_hi:[1,0]
	v_pk_add_f32 v[154:155], v[154:155], 1.0 op_sel_hi:[1,0]
	v_rcp_f32_e32 v156, v156
	v_rcp_f32_e32 v157, v157
	v_rcp_f32_e32 v154, v154
	v_rcp_f32_e32 v155, v155
	v_pk_mul_f32 v[158:159], v[94:95], v[130:131] op_sel_hi:[1,0]
	v_pk_mul_f32 v[134:135], v[134:135], v[156:157]
	v_pk_mul_f32 v[156:157], v[124:125], v[130:131] op_sel_hi:[1,0]
	v_pk_mul_f32 v[132:133], v[132:133], v[154:155]
	v_pk_mul_f32 v[154:155], v[160:161], v[134:135]
	v_pk_mul_f32 v[134:135], v[162:163], s[30:31] op_sel_hi:[1,0]
	v_pk_mul_f32 v[132:133], v[158:159], v[132:133]
	v_exp_f32_e32 v134, v134
	v_exp_f32_e32 v135, v135
	v_pk_mul_f32 v[158:159], v[156:157], s[30:31] op_sel_hi:[1,0]
	ds_bpermute_b32 v146, v139, v140
	v_exp_f32_e32 v158, v158
	v_exp_f32_e32 v159, v159
	v_pk_add_f32 v[134:135], v[134:135], 1.0 op_sel_hi:[1,0]
	ds_bpermute_b32 v139, v139, v142
	v_rcp_f32_e32 v134, v134
	v_rcp_f32_e32 v135, v135
	v_pk_add_f32 v[158:159], v[158:159], 1.0 op_sel_hi:[1,0]
	v_pk_mul_f32 v[164:165], v[90:91], v[130:131] op_sel_hi:[1,0]
	v_rcp_f32_e32 v158, v158
	v_rcp_f32_e32 v159, v159
	v_pk_mul_f32 v[134:135], v[162:163], v[134:135]
	v_pk_mul_f32 v[130:131], v[92:93], v[130:131] op_sel_hi:[1,0]
	v_pk_mul_f32 v[160:161], v[164:165], v[134:135]
	v_pk_mul_f32 v[134:135], v[156:157], v[158:159]
	s_waitcnt lgkmcnt(1)
	v_add_f32_e32 v143, v140, v146
	v_pk_mul_f32 v[156:157], v[130:131], v[134:135]
	v_lshrrev_b32_e32 v131, 3, v136
	s_waitcnt lgkmcnt(0)
	v_add_f32_e32 v139, v142, v139
	v_lshlrev_b32_e32 v130, 7, v136
	v_and_b32_e32 v131, 14, v131
	ds_bpermute_b32 v153, v168, v152
	ds_bpermute_b32 v151, v168, v150
	ds_bpermute_b32 v149, v168, v148
	ds_bpermute_b32 v146, v168, v145
	ds_bpermute_b32 v144, v168, v143
	ds_bpermute_b32 v142, v168, v141
	ds_bpermute_b32 v140, v168, v139
	v_and_b32_e32 v130, 0xffffc000, v130
	v_lshlrev_b32_e32 v134, 6, v136
	v_add_lshl_u32 v147, v131, v138, 10
	v_lshlrev_b32_e32 v131, 2, v136
	v_and_or_b32 v134, v134, s69, v137
	v_and_b32_e32 v131, 32, v131
	v_add_u32_e32 v130, v147, v130
	v_bitop3_b32 v130, v130, v134, v131 bitop3:0xf6
	v_ashrrev_i32_e32 v131, 31, v130
	v_lshl_add_u64 v[134:135], s[50:51], 0, v[130:131]
	v_cvt_pk_bf16_f32 v130, v132, v133
	v_cvt_pk_bf16_f32 v131, v154, v155
	v_cvt_pk_bf16_f32 v132, v160, v161
	v_cvt_pk_bf16_f32 v133, v156, v157
	v_lshl_add_u64 v[170:171], v[134:135], 0, 0
	s_cbranch_vccz .LBB0_2128
	global_store_dwordx4 v[134:135], v[130:133], off
	s_mov_b64 s[10:11], 0
